# v076: v075 + diff fast path: tile t+1 row-sum adds spread three per gap over the P.V(t+1) MFMAs (were partly exposed in front of them)
# baseline (speedup 1.0000x reference)
; #define LAS __attribute__((address_space(3)))
; template <int DQK, int DKA, int DV> ...
;     ...
;         if (64 * t <= qlast) {
;             f32x16 p0, p1; s16x4 vlo[8], vhi[8]; bf16x8 pf[4];
;             LAS const unsigned char* vb = lds + C::VOFF + (t & 3) * C::VBYTES + voff;
;             __builtin_amdgcn_sched_barrier(0);
;             __builtin_amdgcn_s_setprio(3);
; #pragma unroll
;             for (int d0 = 0; d0 < ND; ++d0) {
;                 if (d0 == 0) { p0 = MFMA32(kf[0], qr[0], negm); p1 = MFMA32(kf[1], qr[0], negm); }
;                 else { p0 = MFMA32(kf[2 * d0], qr[d0], p0); p1 = MFMA32(kf[2 * d0 + 1], qr[d0], p1); }
;             }
;             __builtin_amdgcn_s_setprio(0);
;             __builtin_amdgcn_sched_barrier(0);
;             ATT_VFRAG(0);
;             __builtin_amdgcn_sched_barrier(0);
;             if (64 * t + 63 > q0 + 32 * wid) {
;                 const int kvb = 64 * t + 4 * hi;
; #pragma unroll
;                 for (int i = 0; i < 16; ++i) { const int kv = kvb + (i & 3) + 8 * (i >> 2); if (kv > qabs) p0[i] = -INFINITY; if (kv + 32 > qabs) p1[i] = -INFINITY; }
;             }
;             float mxa = MAX3F(p0[0], p0[1], p1[0]), mxb = MAX3F(p0[2], p0[3], p1[1]); mxa = MAX3F(mxa, p1[2], p1[3]);
; #pragma unroll
;             for (int i = 4; i < 16; i += 4) { mxa = MAX3F(mxa, p0[i], p0[i + 1]); mxb = MAX3F(mxb, p0[i + 2], p0[i + 3]); mxa = MAX3F(mxa, p1[i], p1[i + 1]); mxb = MAX3F(mxb, p1[i + 2], p1[i + 3]); }
;             float mx = fmaxf(mxa, mxb);
;             { auto rr = __builtin_amdgcn_permlane32_swap(__float_as_uint(mx), __float_as_uint(mx), false, false); mx = fmaxf(__uint_as_float(rr[0]), __uint_as_float(rr[1])); }
;             if (!NEGM) mx -= m;
;             if (t == 0) {
;                 m = mx;
;                 if (NEGM) {
; #pragma unroll
;                     for (int i = 0; i < 16; ++i) { p0[i] -= mx; p1[i] -= mx; }
; #pragma unroll
;                     for (int i = 0; i < 16; ++i) negm[i] = -m;
;                 }
;             } else if (__any(mx > RESC_THR)) {
;     ...
;             { float rs = 0.f;
; #pragma unroll
;               for (int i = 0; i < 16; ++i) { p0[i] = __builtin_amdgcn_exp2f(NEGM ? p0[i] : p0[i] - m); p1[i] = __builtin_amdgcn_exp2f(NEGM ? p1[i] : p1[i] - m); rs += p0[i] + p1[i]; }
;               l += rs;
; #pragma unroll
;               for (int s = 0; s < 2; ++s) { u32x4 w0, w1;
.Lfast_d_qk:
	v_mfma_f32_32x32x16_bf16 v[80:95], v[144:147], v[112:115], v[0:15]
	ds_read_b128 v[144:147], v249
	v_mfma_f32_32x32x16_bf16 v[96:111], v[152:155], v[112:115], v[0:15]
	ds_read_b128 v[152:155], v249 offset:4608
	v_mfma_f32_32x32x16_bf16 v[80:95], v[140:143], v[116:119], v[80:95]
	ds_read_b128 v[140:143], v249 offset:32
	v_mfma_f32_32x32x16_bf16 v[96:111], v[148:151], v[116:119], v[96:111]
	ds_read_b128 v[148:151], v249 offset:4640
	v_mfma_f32_32x32x16_bf16 v[80:95], v[156:159], v[120:123], v[80:95]
	ds_read_b128 v[156:159], v249 offset:64
	v_mfma_f32_32x32x16_bf16 v[96:111], v[168:171], v[120:123], v[96:111]
	ds_read_b128 v[168:171], v249 offset:4672
	v_mfma_f32_32x32x16_bf16 v[80:95], v[160:163], v[124:127], v[80:95]
	ds_read_b128 v[160:163], v249 offset:96
	v_mfma_f32_32x32x16_bf16 v[96:111], v[164:167], v[124:127], v[96:111]
	ds_read_b128 v[164:167], v249 offset:4704
	s_setprio 0
	s_add_i32 s80, s1, -1
	s_add_i32 s23, s1, -2
	s_and_b32 s22, s80, 3
	s_mulk_i32 s22, 0x2400
	v_add_u32_e32 v253, s22, v217
	s_waitcnt vmcnt(0)
	ds_write_b128 v253, v[128:131]
	s_and_b32 s22, s23, 3
	s_mulk_i32 s22, 0x5000
	v_add_u32_e32 v253, s22, v227
	ds_write_b128 v253, v[132:135] offset:36864
	ds_write_b128 v253, v[136:139] offset:47104
	global_load_dwordx4 v[128:131], v[218:219], off
	v_add_co_u32_e32 v254, vcc, 0x2000, v220
	s_nop 1
	v_addc_co_u32_e32 v255, vcc, 0, v221, vcc
	global_load_dwordx4 v[132:135], v[220:221], off
	global_load_dwordx4 v[136:139], v[254:255], off
	v_max_f32_e32 v232, v81, v81
	v_max_f32_e32 v233, v80, v80
	v_max_f32_e32 v232, v233, v232
	v_max3_f32 v233, v82, v83, v97
	v_max3_f32 v232, v232, v96, v98
	v_max3_f32 v232, v232, v99, v84
	v_max3_f32 v233, v233, v86, v87
	v_max3_f32 v232, v232, v85, v100
	v_max3_f32 v233, v233, v102, v103
	v_max3_f32 v232, v232, v101, v88
	v_max3_f32 v233, v233, v90, v91
	v_max3_f32 v232, v232, v89, v104
	v_max3_f32 v233, v233, v106, v107
	v_max3_f32 v232, v232, v105, v92
	v_max3_f32 v233, v233, v94, v95
	v_max3_f32 v232, v232, v93, v108
	v_max3_f32 v233, v233, v110, v111
	v_max3_f32 v232, v232, v109, v233
	v_mov_b32_e32 v233, v232
	s_nop 1
	v_permlane32_swap_b32_e32 v232, v233
	v_max_f32_e32 v233, v233, v233
	v_max_f32_e32 v232, v232, v232
	v_max_f32_e32 v232, v232, v233
	v_cmp_lt_f32_e32 vcc, s62, v232
	s_cbranch_vccnz .Lfast_d_bail1
	s_waitcnt lgkmcnt(0)
	v_exp_f32_e32 v80, v80
	v_exp_f32_e32 v96, v96
	v_exp_f32_e32 v81, v81
	v_exp_f32_e32 v97, v97
	v_mfma_f32_32x32x16_bf16 v[172:187], v[144:147], v[112:115], v[0:15]
	ds_read_b64_tr_b16 v[144:145], v210 offset:36864
	ds_read_b64_tr_b16 v[146:147], v210 offset:39424
	v_exp_f32_e32 v82, v82
	v_exp_f32_e32 v98, v98
	v_exp_f32_e32 v83, v83
	v_exp_f32_e32 v99, v99
	v_mfma_f32_32x32x16_bf16 v[188:203], v[152:155], v[112:115], v[0:15]
	ds_read_b64_tr_b16 v[152:153], v210 offset:36928
	ds_read_b64_tr_b16 v[154:155], v210 offset:39488
	v_exp_f32_e32 v84, v84
	v_exp_f32_e32 v100, v100
	v_exp_f32_e32 v85, v85
	v_exp_f32_e32 v101, v101
	v_mfma_f32_32x32x16_bf16 v[172:187], v[140:143], v[116:119], v[172:187]
	ds_read_b64_tr_b16 v[140:141], v210 offset:41984
	ds_read_b64_tr_b16 v[142:143], v210 offset:44544
	v_exp_f32_e32 v86, v86
	v_exp_f32_e32 v102, v102
	v_exp_f32_e32 v87, v87
	v_exp_f32_e32 v103, v103
	v_mfma_f32_32x32x16_bf16 v[188:203], v[148:151], v[116:119], v[188:203]
	ds_read_b64_tr_b16 v[148:149], v210 offset:42048
	ds_read_b64_tr_b16 v[150:151], v210 offset:44608
	v_exp_f32_e32 v88, v88
	v_exp_f32_e32 v104, v104
	v_exp_f32_e32 v89, v89
	v_exp_f32_e32 v105, v105
	v_mfma_f32_32x32x16_bf16 v[172:187], v[156:159], v[120:123], v[172:187]
	ds_read_b64_tr_b16 v[156:157], v210 offset:47104
	ds_read_b64_tr_b16 v[158:159], v210 offset:49664
	v_exp_f32_e32 v90, v90
	v_exp_f32_e32 v106, v106
	v_exp_f32_e32 v91, v91
	v_exp_f32_e32 v107, v107
	v_mfma_f32_32x32x16_bf16 v[188:203], v[168:171], v[120:123], v[188:203]
	ds_read_b64_tr_b16 v[168:169], v210 offset:47168
	ds_read_b64_tr_b16 v[170:171], v210 offset:49728
	v_exp_f32_e32 v92, v92
	v_exp_f32_e32 v108, v108
	v_exp_f32_e32 v93, v93
	v_exp_f32_e32 v109, v109
	v_mfma_f32_32x32x16_bf16 v[172:187], v[160:163], v[124:127], v[172:187]
	ds_read_b64_tr_b16 v[160:161], v210 offset:52224
	ds_read_b64_tr_b16 v[162:163], v210 offset:54784
	v_exp_f32_e32 v94, v94
	v_exp_f32_e32 v110, v110
	v_exp_f32_e32 v95, v95
	v_exp_f32_e32 v111, v111
	v_mfma_f32_32x32x16_bf16 v[188:203], v[164:167], v[124:127], v[188:203]
	ds_read_b64_tr_b16 v[164:165], v210 offset:52288
	ds_read_b64_tr_b16 v[166:167], v210 offset:54848
	v_cvt_pk_bf16_f32 v232, v80, v81
	v_cvt_pk_bf16_f32 v233, v82, v83
	v_cvt_pk_bf16_f32 v234, v84, v85
	v_cvt_pk_bf16_f32 v235, v86, v87
	v_cvt_pk_bf16_f32 v236, v96, v97
	v_cvt_pk_bf16_f32 v237, v98, v99
	v_cvt_pk_bf16_f32 v238, v100, v101
	v_cvt_pk_bf16_f32 v239, v102, v103
	v_cvt_pk_bf16_f32 v240, v88, v89
	v_cvt_pk_bf16_f32 v241, v90, v91
	v_cvt_pk_bf16_f32 v242, v92, v93
	v_cvt_pk_bf16_f32 v243, v94, v95
	v_cvt_pk_bf16_f32 v244, v104, v105
	v_cvt_pk_bf16_f32 v245, v106, v107
	v_cvt_pk_bf16_f32 v246, v108, v109
	v_cvt_pk_bf16_f32 v247, v110, v111
	v_max_f32_e32 v250, v173, v173
	v_max_f32_e32 v251, v172, v172
	v_max_f32_e32 v250, v251, v250
	v_max3_f32 v251, v174, v175, v189
	v_max3_f32 v250, v250, v188, v190
	v_max3_f32 v250, v250, v191, v176
	v_max3_f32 v251, v251, v178, v179
	v_max3_f32 v250, v250, v177, v192
	v_max3_f32 v251, v251, v194, v195
	v_max3_f32 v250, v250, v193, v180
	v_max3_f32 v251, v251, v182, v183
	v_max3_f32 v250, v250, v181, v196
	v_max3_f32 v251, v251, v198, v199
	v_max3_f32 v250, v250, v197, v184
	v_max3_f32 v251, v251, v186, v187
	v_max3_f32 v250, v250, v185, v200
	v_max3_f32 v251, v251, v202, v203
	v_max3_f32 v250, v250, v201, v251
	v_mov_b32_e32 v251, v250
	s_nop 1
	v_permlane32_swap_b32_e32 v250, v251
	v_max_f32_e32 v251, v251, v251
	v_max_f32_e32 v250, v250, v250
	v_max_f32_e32 v250, v250, v251
	v_cmp_lt_f32_e32 vcc, s62, v250
	s_cbranch_vccnz .Lfast_d_bail2
; __device__ __forceinline__ unsigned cvtpk_s(float lo, float hi) { f32x2_t v = {lo, hi}; bf16x2_t b = __builtin_convertvector(v, bf16x2_t); return __builtin_bit_cast(unsigned, b); }
; #define ATT_KFRAG(slot) do { LAS const unsigned char* kb_ = lds + (slot) * C::KBYTES + koff; \
;     _Pragma("unroll") for (int d0 = 0; d0 < ND; ++d0) { kf[2 * d0] = *(LAS const bf16x8*)(kb_ + 32 * d0); kf[2 * d0 + 1] = *(LAS const bf16x8*)(kb_ + 32 * KP + 32 * d0); } } while (0)
; #define ATT_VFRAG(vv) do { _Pragma("unroll") for (int j = 0; j < 2; ++j) _Pragma("unroll") for (int s4 = 0; s4 < 4; ++s4) { \
;         vlo[j * 4 + s4] = vtr(vb + (16 * s4) * VP + 64 * ((vv) + j)); vhi[j * 4 + s4] = vtr(vb + (16 * s4 + 8) * VP + 64 * ((vv) + j)); } } while (0)
; template <int DQK, int DKA, int DV> ...
;     ...
;             { float rs = 0.f;
; #pragma unroll
;               for (int i = 0; i < 16; ++i) { p0[i] = __builtin_amdgcn_exp2f(NEGM ? p0[i] : p0[i] - m); p1[i] = __builtin_amdgcn_exp2f(NEGM ? p1[i] : p1[i] - m); rs += p0[i] + p1[i]; }
;               l += rs;
; #pragma unroll
;               for (int s = 0; s < 2; ++s) { u32x4 w0, w1;
;                 w0.x = cvtpk_s(p0[8 * s], p0[8 * s + 1]); w0.y = cvtpk_s(p0[8 * s + 2], p0[8 * s + 3]); w0.z = cvtpk_s(p0[8 * s + 4], p0[8 * s + 5]); w0.w = cvtpk_s(p0[8 * s + 6], p0[8 * s + 7]);
;                 w1.x = cvtpk_s(p1[8 * s], p1[8 * s + 1]); w1.y = cvtpk_s(p1[8 * s + 2], p1[8 * s + 3]); w1.z = cvtpk_s(p1[8 * s + 4], p1[8 * s + 5]); w1.w = cvtpk_s(p1[8 * s + 6], p1[8 * s + 7]);
;                 pf[s] = __builtin_bit_cast(bf16x8, w0); pf[2 + s] = __builtin_bit_cast(bf16x8, w1); } }
;             __builtin_amdgcn_sched_barrier(0);
;             if (NV == 2) {
;                 __builtin_amdgcn_s_setprio(3); ATT_PV(0); __builtin_amdgcn_s_setprio(0);
;                 __builtin_amdgcn_sched_barrier(0);
;                 if (t + 1 < NT) ATT_KFRAG(ks1);
;             } else {
;                 __builtin_amdgcn_s_setprio(3); ATT_PV(0); __builtin_amdgcn_s_setprio(0);
;                 __builtin_amdgcn_sched_barrier(0);
;                 ATT_VFRAG(2);
;                 __builtin_amdgcn_sched_barrier(0);
;                 __builtin_amdgcn_s_setprio(3); ATT_PV(2); __builtin_amdgcn_s_setprio(0);
;                 __builtin_amdgcn_sched_barrier(0);
;                 if (t + 1 < NT) ATT_KFRAG(ks1);
;             }
	s_setprio 0
	s_waitcnt lgkmcnt(0)
	v_mfma_f32_32x32x16_bf16 v[32:47], v[144:147], v[232:235], v[32:47]
	v_lshl_add_u64 v[218:219], v[218:219], 0, s[10:11]
	v_lshl_add_u64 v[220:221], v[220:221], 0, s[8:9]
	s_add_i32 s23, s1, -1
	s_and_b32 s22, s1, 3
	s_mulk_i32 s22, 0x2400
	v_add_u32_e32 v253, s22, v217
	s_waitcnt vmcnt(0)
	ds_write_b128 v253, v[128:131]
	s_and_b32 s22, s23, 3
	s_mulk_i32 s22, 0x5000
	v_mfma_f32_32x32x16_bf16 v[16:31], v[152:155], v[232:235], v[16:31]
	v_add_u32_e32 v253, s22, v227
	ds_write_b128 v253, v[132:135] offset:36864
	ds_write_b128 v253, v[136:139] offset:47104
	global_load_dwordx4 v[128:131], v[218:219], off
	v_add_co_u32_e32 v254, vcc, 0x2000, v220
	s_nop 1
	v_addc_co_u32_e32 v255, vcc, 0, v221, vcc
	global_load_dwordx4 v[132:135], v[220:221], off
	global_load_dwordx4 v[136:139], v[254:255], off
	v_add_f32_e32 v80, v80, v96
	v_add_f32_e32 v81, v81, v97
	v_add_f32_e32 v80, 0, v80
	v_add_f32_e32 v82, v82, v98
	v_mfma_f32_32x32x16_bf16 v[32:47], v[140:143], v[240:243], v[32:47]
	v_add_f32_e32 v80, v81, v80
	v_add_f32_e32 v83, v83, v99
	v_add_f32_e32 v80, v82, v80
	v_add_f32_e32 v84, v84, v100
	v_add_f32_e32 v80, v83, v80
	v_add_f32_e32 v85, v85, v101
	v_add_f32_e32 v80, v84, v80
	v_add_f32_e32 v86, v86, v102
	v_add_f32_e32 v80, v85, v80
	v_add_f32_e32 v87, v87, v103
	v_mfma_f32_32x32x16_bf16 v[16:31], v[148:151], v[240:243], v[16:31]
	v_add_f32_e32 v80, v86, v80
	v_add_f32_e32 v88, v88, v104
	v_add_f32_e32 v80, v87, v80
	v_add_f32_e32 v89, v89, v105
	v_add_f32_e32 v80, v88, v80
	v_add_f32_e32 v90, v90, v106
	v_add_f32_e32 v80, v89, v80
	v_add_f32_e32 v91, v91, v107
	v_add_f32_e32 v80, v90, v80
	v_add_f32_e32 v92, v92, v108
	v_mfma_f32_32x32x16_bf16 v[32:47], v[156:159], v[236:239], v[32:47]
	v_add_f32_e32 v80, v91, v80
	v_add_f32_e32 v93, v93, v109
	v_add_f32_e32 v80, v92, v80
	v_add_f32_e32 v94, v94, v110
	v_add_f32_e32 v80, v93, v80
	v_add_f32_e32 v95, v95, v111
	v_add_f32_e32 v80, v94, v80
	v_add_f32_e32 v80, v95, v80
	v_add_f32_e32 v231, v231, v80
	ds_read_b64_tr_b16 v[80:81], v210 offset:36992
	ds_read_b64_tr_b16 v[82:83], v210 offset:39552
	ds_read_b64_tr_b16 v[84:85], v210 offset:37056
	ds_read_b64_tr_b16 v[86:87], v210 offset:39616
	v_mfma_f32_32x32x16_bf16 v[16:31], v[168:171], v[236:239], v[16:31]
	ds_read_b64_tr_b16 v[88:89], v210 offset:42112
	ds_read_b64_tr_b16 v[90:91], v210 offset:44672
	ds_read_b64_tr_b16 v[92:93], v210 offset:42176
	ds_read_b64_tr_b16 v[94:95], v210 offset:44736
	ds_read_b64_tr_b16 v[96:97], v210 offset:47232
	ds_read_b64_tr_b16 v[98:99], v210 offset:49792
	ds_read_b64_tr_b16 v[100:101], v210 offset:47296
	ds_read_b64_tr_b16 v[102:103], v210 offset:49856
	v_mfma_f32_32x32x16_bf16 v[32:47], v[160:163], v[244:247], v[32:47]
	ds_read_b64_tr_b16 v[104:105], v210 offset:52352
	ds_read_b64_tr_b16 v[106:107], v210 offset:54912
	ds_read_b64_tr_b16 v[108:109], v210 offset:52416
	ds_read_b64_tr_b16 v[110:111], v210 offset:54976
	v_exp_f32_e32 v172, v172
	v_exp_f32_e32 v188, v188
	v_mfma_f32_32x32x16_bf16 v[16:31], v[164:167], v[244:247], v[16:31]
	v_exp_f32_e32 v173, v173
	v_exp_f32_e32 v189, v189
	v_exp_f32_e32 v174, v174
	v_exp_f32_e32 v190, v190
	s_waitcnt lgkmcnt(14)
	v_mfma_f32_32x32x16_bf16 v[64:79], v[80:83], v[232:235], v[64:79]
	ds_read_b64_tr_b16 v[144:145], v252 offset:36864
	ds_read_b64_tr_b16 v[146:147], v252 offset:39424
	v_exp_f32_e32 v175, v175
	v_exp_f32_e32 v191, v191
	v_exp_f32_e32 v176, v176
	v_exp_f32_e32 v192, v192
	s_waitcnt lgkmcnt(14)
	v_mfma_f32_32x32x16_bf16 v[48:63], v[84:87], v[232:235], v[48:63]
	ds_read_b64_tr_b16 v[152:153], v252 offset:36928
	ds_read_b64_tr_b16 v[154:155], v252 offset:39488
	v_exp_f32_e32 v177, v177
	v_exp_f32_e32 v193, v193
	v_exp_f32_e32 v178, v178
	v_exp_f32_e32 v194, v194
	s_waitcnt lgkmcnt(14)
	v_mfma_f32_32x32x16_bf16 v[64:79], v[88:91], v[240:243], v[64:79]
	ds_read_b64_tr_b16 v[140:141], v252 offset:41984
	ds_read_b64_tr_b16 v[142:143], v252 offset:44544
	v_exp_f32_e32 v179, v179
	v_exp_f32_e32 v195, v195
	v_exp_f32_e32 v180, v180
	s_waitcnt lgkmcnt(14)
	v_mfma_f32_32x32x16_bf16 v[48:63], v[92:95], v[240:243], v[48:63]
	ds_read_b64_tr_b16 v[148:149], v252 offset:42048
	ds_read_b64_tr_b16 v[150:151], v252 offset:44608
	v_exp_f32_e32 v196, v196
	v_exp_f32_e32 v181, v181
	v_exp_f32_e32 v197, v197
	s_waitcnt lgkmcnt(14)
	v_mfma_f32_32x32x16_bf16 v[64:79], v[96:99], v[236:239], v[64:79]
	ds_read_b64_tr_b16 v[156:157], v252 offset:47104
	ds_read_b64_tr_b16 v[158:159], v252 offset:49664
	v_exp_f32_e32 v182, v182
	v_exp_f32_e32 v198, v198
	v_exp_f32_e32 v183, v183
	s_waitcnt lgkmcnt(14)
	v_mfma_f32_32x32x16_bf16 v[48:63], v[100:103], v[236:239], v[48:63]
	ds_read_b64_tr_b16 v[168:169], v252 offset:47168
	ds_read_b64_tr_b16 v[170:171], v252 offset:49728
	v_exp_f32_e32 v199, v199
	v_exp_f32_e32 v184, v184
	v_exp_f32_e32 v200, v200
	s_waitcnt lgkmcnt(14)
; __device__ __forceinline__ unsigned cvtpk_s(float lo, float hi) { f32x2_t v = {lo, hi}; bf16x2_t b = __builtin_convertvector(v, bf16x2_t); return __builtin_bit_cast(unsigned, b); }
; #define ATT_KFRAG(slot) do { LAS const unsigned char* kb_ = lds + (slot) * C::KBYTES + koff; \
;     _Pragma("unroll") for (int d0 = 0; d0 < ND; ++d0) { kf[2 * d0] = *(LAS const bf16x8*)(kb_ + 32 * d0); kf[2 * d0 + 1] = *(LAS const bf16x8*)(kb_ + 32 * KP + 32 * d0); } } while (0)
; #define ATT_VFRAG(vv) do { _Pragma("unroll") for (int j = 0; j < 2; ++j) _Pragma("unroll") for (int s4 = 0; s4 < 4; ++s4) { \
;         vlo[j * 4 + s4] = vtr(vb + (16 * s4) * VP + 64 * ((vv) + j)); vhi[j * 4 + s4] = vtr(vb + (16 * s4 + 8) * VP + 64 * ((vv) + j)); } } while (0)
; template <int DQK, int DKA, int DV> ...
;     ...
;             { float rs = 0.f;
; #pragma unroll
;               for (int i = 0; i < 16; ++i) { p0[i] = __builtin_amdgcn_exp2f(NEGM ? p0[i] : p0[i] - m); p1[i] = __builtin_amdgcn_exp2f(NEGM ? p1[i] : p1[i] - m); rs += p0[i] + p1[i]; }
;               l += rs;
; #pragma unroll
;               for (int s = 0; s < 2; ++s) { u32x4 w0, w1;
;                 w0.x = cvtpk_s(p0[8 * s], p0[8 * s + 1]); w0.y = cvtpk_s(p0[8 * s + 2], p0[8 * s + 3]); w0.z = cvtpk_s(p0[8 * s + 4], p0[8 * s + 5]); w0.w = cvtpk_s(p0[8 * s + 6], p0[8 * s + 7]);
;                 w1.x = cvtpk_s(p1[8 * s], p1[8 * s + 1]); w1.y = cvtpk_s(p1[8 * s + 2], p1[8 * s + 3]); w1.z = cvtpk_s(p1[8 * s + 4], p1[8 * s + 5]); w1.w = cvtpk_s(p1[8 * s + 6], p1[8 * s + 7]);
;                 pf[s] = __builtin_bit_cast(bf16x8, w0); pf[2 + s] = __builtin_bit_cast(bf16x8, w1); } }
;             __builtin_amdgcn_sched_barrier(0);
;             if (NV == 2) {
;                 __builtin_amdgcn_s_setprio(3); ATT_PV(0); __builtin_amdgcn_s_setprio(0);
;                 __builtin_amdgcn_sched_barrier(0);
;                 if (t + 1 < NT) ATT_KFRAG(ks1);
;             } else {
;                 __builtin_amdgcn_s_setprio(3); ATT_PV(0); __builtin_amdgcn_s_setprio(0);
;                 __builtin_amdgcn_sched_barrier(0);
;                 ATT_VFRAG(2);
;                 __builtin_amdgcn_sched_barrier(0);
;                 __builtin_amdgcn_s_setprio(3); ATT_PV(2); __builtin_amdgcn_s_setprio(0);
;                 __builtin_amdgcn_sched_barrier(0);
;                 if (t + 1 < NT) ATT_KFRAG(ks1);
;             }
	v_mfma_f32_32x32x16_bf16 v[64:79], v[104:107], v[244:247], v[64:79]
	ds_read_b64_tr_b16 v[160:161], v252 offset:52224
	ds_read_b64_tr_b16 v[162:163], v252 offset:54784
	v_exp_f32_e32 v185, v185
	v_exp_f32_e32 v201, v201
	v_exp_f32_e32 v186, v186
	s_waitcnt lgkmcnt(14)
	v_mfma_f32_32x32x16_bf16 v[48:63], v[108:111], v[244:247], v[48:63]
	ds_read_b64_tr_b16 v[164:165], v252 offset:52288
	ds_read_b64_tr_b16 v[166:167], v252 offset:54848
	v_exp_f32_e32 v202, v202
	v_exp_f32_e32 v187, v187
	v_exp_f32_e32 v203, v203
	s_setprio 0
	v_cvt_pk_bf16_f32 v232, v172, v173
	v_cvt_pk_bf16_f32 v233, v174, v175
	v_cvt_pk_bf16_f32 v234, v176, v177
	v_cvt_pk_bf16_f32 v235, v178, v179
	v_cvt_pk_bf16_f32 v236, v188, v189
	v_cvt_pk_bf16_f32 v237, v190, v191
	v_cvt_pk_bf16_f32 v238, v192, v193
	v_cvt_pk_bf16_f32 v239, v194, v195
	v_cvt_pk_bf16_f32 v240, v180, v181
	v_cvt_pk_bf16_f32 v241, v182, v183
	v_cvt_pk_bf16_f32 v242, v184, v185
	v_cvt_pk_bf16_f32 v243, v186, v187
	v_cvt_pk_bf16_f32 v244, v196, v197
	v_cvt_pk_bf16_f32 v245, v198, v199
	v_cvt_pk_bf16_f32 v246, v200, v201
	v_cvt_pk_bf16_f32 v247, v202, v203
	s_waitcnt lgkmcnt(0)
	v_mfma_f32_32x32x16_bf16 v[32:47], v[144:147], v[232:235], v[32:47]
	ds_read_b64_tr_b16 v[80:81], v252 offset:36992
	ds_read_b64_tr_b16 v[82:83], v252 offset:39552
	ds_read_b64_tr_b16 v[84:85], v252 offset:37056
	ds_read_b64_tr_b16 v[86:87], v252 offset:39616
	v_add_f32_e32 v172, v172, v188
	v_add_f32_e32 v173, v173, v189
	v_add_f32_e32 v172, 0, v172
	v_mfma_f32_32x32x16_bf16 v[16:31], v[152:155], v[232:235], v[16:31]
	ds_read_b64_tr_b16 v[88:89], v252 offset:42112
	ds_read_b64_tr_b16 v[90:91], v252 offset:44672
	ds_read_b64_tr_b16 v[92:93], v252 offset:42176
	ds_read_b64_tr_b16 v[94:95], v252 offset:44736
	v_add_f32_e32 v174, v174, v190
	v_add_f32_e32 v172, v173, v172
	v_add_f32_e32 v175, v175, v191
	v_mfma_f32_32x32x16_bf16 v[32:47], v[140:143], v[240:243], v[32:47]
	ds_read_b64_tr_b16 v[96:97], v252 offset:47232
	ds_read_b64_tr_b16 v[98:99], v252 offset:49792
	ds_read_b64_tr_b16 v[100:101], v252 offset:47296
	ds_read_b64_tr_b16 v[102:103], v252 offset:49856
	v_add_f32_e32 v172, v174, v172
	v_add_f32_e32 v176, v176, v192
	v_add_f32_e32 v172, v175, v172
	v_mfma_f32_32x32x16_bf16 v[16:31], v[148:151], v[240:243], v[16:31]
	ds_read_b64_tr_b16 v[104:105], v252 offset:52352
	ds_read_b64_tr_b16 v[106:107], v252 offset:54912
	ds_read_b64_tr_b16 v[108:109], v252 offset:52416
	ds_read_b64_tr_b16 v[110:111], v252 offset:54976
	v_add_f32_e32 v177, v177, v193
	v_add_f32_e32 v172, v176, v172
	v_add_f32_e32 v178, v178, v194
	v_mfma_f32_32x32x16_bf16 v[32:47], v[156:159], v[236:239], v[32:47]
	v_add_f32_e32 v172, v177, v172
	v_add_f32_e32 v179, v179, v195
	v_add_f32_e32 v172, v178, v172
	v_mfma_f32_32x32x16_bf16 v[16:31], v[168:171], v[236:239], v[16:31]
	v_add_f32_e32 v180, v180, v196
	v_add_f32_e32 v172, v179, v172
	v_add_f32_e32 v181, v181, v197
	v_mfma_f32_32x32x16_bf16 v[32:47], v[160:163], v[244:247], v[32:47]
	v_add_f32_e32 v172, v180, v172
	v_add_f32_e32 v182, v182, v198
	v_add_f32_e32 v172, v181, v172
	v_mfma_f32_32x32x16_bf16 v[16:31], v[164:167], v[244:247], v[16:31]
	v_add_f32_e32 v183, v183, v199
	v_add_f32_e32 v172, v182, v172
	v_add_f32_e32 v184, v184, v200
	s_add_i32 s1, s1, 2
	s_addk_i32 s79, 0x80
	s_add_i32 s22, s1, -4
	s_and_b32 s22, s22, 3
	s_mulk_i32 s22, 0x2400
	v_add_u32_e32 v249, s22, v226
	s_waitcnt lgkmcnt(0)
	v_mfma_f32_32x32x16_bf16 v[64:79], v[80:83], v[232:235], v[64:79]
	ds_read_b128 v[144:147], v249
	ds_read_b128 v[152:155], v249 offset:4608
	v_add_f32_e32 v172, v183, v172
	v_add_f32_e32 v185, v185, v201
	v_add_f32_e32 v172, v184, v172
	v_mfma_f32_32x32x16_bf16 v[48:63], v[84:87], v[232:235], v[48:63]
	ds_read_b128 v[140:143], v249 offset:32
	ds_read_b128 v[148:151], v249 offset:4640
	v_add_f32_e32 v186, v186, v202
	v_add_f32_e32 v172, v185, v172
	v_add_f32_e32 v187, v187, v203
	v_mfma_f32_32x32x16_bf16 v[64:79], v[88:91], v[240:243], v[64:79]
	ds_read_b128 v[156:159], v249 offset:64
	ds_read_b128 v[168:171], v249 offset:4672
	v_add_f32_e32 v172, v186, v172
	v_add_f32_e32 v172, v187, v172
	v_add_f32_e32 v231, v231, v172
	v_mfma_f32_32x32x16_bf16 v[48:63], v[92:95], v[240:243], v[48:63]
	ds_read_b128 v[160:163], v249 offset:96
	ds_read_b128 v[164:167], v249 offset:4704
	v_mfma_f32_32x32x16_bf16 v[64:79], v[96:99], v[236:239], v[64:79]
	v_lshl_add_u64 v[218:219], v[218:219], 0, s[10:11]
	v_mfma_f32_32x32x16_bf16 v[48:63], v[100:103], v[236:239], v[48:63]
	v_lshl_add_u64 v[220:221], v[220:221], 0, s[8:9]
	v_mfma_f32_32x32x16_bf16 v[64:79], v[104:107], v[244:247], v[64:79]
	v_mfma_f32_32x32x16_bf16 v[48:63], v[108:111], v[244:247], v[48:63]
	s_setprio 0
	s_add_i32 s23, s1, 1
	s_cmp_lt_u32 s23, s16
	s_cbranch_scc0 .Lfast_d_x
	s_add_i32 s50, s1, -4
	s_and_b32 s22, s50, 3
	s_mulk_i32 s22, 0x5000
	v_add_u32_e32 v210, s22, v229
	s_add_i32 s51, s1, -3
	s_and_b32 s22, s51, 3
	s_mul_i32 s23, s22, 0x5000
	s_mulk_i32 s22, 0x2400
	v_add_u32_e32 v249, s22, v226
	v_add_u32_e32 v252, s23, v229
	s_waitcnt lgkmcnt(0)
	s_barrier
	s_setprio 3
	s_branch .Lfast_d_qk
